# v043 + window attention tile loops: compiler-inserted full vmcnt(0) drain before each tile barrier removed (the counted vmcnt(4) already covers the tile in use; keeps the 2-tile LDS-DMA prefetch in fl
# speedup vs baseline: 1.0008x; 1.0008x over previous
.LBB0_710:
	s_add_i32 s23, s22, 2
	s_cmp_lt_i32 s23, s63
	s_mov_b64 s[2:3], -1
	s_waitcnt lgkmcnt(0)
	s_barrier
	s_cbranch_scc1 .LBB0_712
	s_lshl_b32 s80, s64, 14
	s_mov_b64 s[2:3], 0

.LBB0_725:
	s_and_b32 s28, s50, 15
	s_lshl_b32 s2, s28, 2
	v_mov_b32_e32 v2, s2
	s_lshl_b32 s2, s50, 4
	s_and_b32 s24, s2, 0xffffff00
	s_ashr_i32 s25, s24, 31
	s_lshl_b64 s[2:3], s[24:25], 12
	s_add_u32 s2, s30, s2
	s_addc_u32 s3, s31, s3
	s_lshl_b32 s26, s28, 8
	s_add_u32 s2, s2, s26
	s_addc_u32 s3, s3, 0
	s_lshl_b32 s29, s50, 6
	s_lshl_b64 s[26:27], s[24:25], 10
	s_and_b32 s29, s29, 0x300
	s_or_b32 s26, s26, s29
	s_add_u32 s54, s34, s26
	v_add_u32_e32 v70, 0xc000, v151
	global_load_dword v157, v2, s[52:53]
	s_addc_u32 s55, s35, s27
	v_lshl_add_u64 v[2:3], s[2:3], 0, v[130:131]
	v_mov_b32_e32 v137, v131
	v_readfirstlane_b32 s2, v70
	v_add_u32_e32 v71, 0xe000, v151
	s_add_u32 s26, s36, s26
	v_lshl_add_u64 v[2:3], v[2:3], 0, v[136:137]
	v_lshl_add_u64 v[66:67], s[54:55], 0, v[132:133]
	s_mov_b32 m0, s2
	v_readfirstlane_b32 s2, v71
	s_addc_u32 s27, s37, s27
	global_load_dwordx4 v[98:101], v[2:3], off
	global_load_dwordx4 v[102:105], v[2:3], off offset:32
	global_load_dwordx4 v[106:109], v[2:3], off offset:64
	global_load_dwordx4 v[110:113], v[2:3], off offset:96
	global_load_dwordx4 v[114:117], v[2:3], off offset:128
	global_load_dwordx4 v[118:121], v[2:3], off offset:160
	global_load_dwordx4 v[122:125], v[2:3], off offset:192
	global_load_dwordx4 v[126:129], v[2:3], off offset:224
	v_lshl_add_u64 v[2:3], v[66:67], 0, s[6:7]
	global_load_lds_dwordx4 v[66:67], off
	s_mov_b32 m0, s2
	v_readfirstlane_b32 s2, v151
	v_add_u32_e32 v72, 0x2000, v151
	global_load_lds_dwordx4 v[2:3], off
	v_lshl_add_u64 v[68:69], s[26:27], 0, v[134:135]
	s_mov_b32 m0, s2
	v_readfirstlane_b32 s2, v72
	v_add_u32_e32 v4, s42, v140
	global_load_lds_dwordx4 v[68:69], off
	v_lshl_add_u64 v[2:3], v[68:69], 0, s[6:7]
	s_mov_b32 m0, s2
	v_readfirstlane_b32 s2, v4
	v_add_u32_e32 v4, s43, v140
	global_load_lds_dwordx4 v[2:3], off
	v_lshl_add_u64 v[2:3], v[66:67], 0, s[8:9]
	s_mov_b32 m0, s2
	v_readfirstlane_b32 s2, v4
	v_add_u32_e32 v4, 0x4000, v151
	global_load_lds_dwordx4 v[2:3], off
	v_lshl_add_u64 v[2:3], v[66:67], 0, s[10:11]
	s_mov_b32 m0, s2
	v_readfirstlane_b32 s2, v4
	v_add_u32_e32 v4, 0x6000, v151
	global_load_lds_dwordx4 v[2:3], off
	v_lshl_add_u64 v[2:3], v[68:69], 0, s[8:9]
	s_mov_b32 m0, s2
	v_readfirstlane_b32 s2, v4
	v_add_u32_e32 v4, s44, v140
	global_load_lds_dwordx4 v[2:3], off
	v_lshl_add_u64 v[2:3], v[68:69], 0, s[10:11]
	s_mov_b32 m0, s2
	v_readfirstlane_b32 s2, v4
	v_add_u32_e32 v4, s45, v140
	global_load_lds_dwordx4 v[2:3], off
	v_lshl_add_u64 v[2:3], v[66:67], 0, s[12:13]
	s_mov_b32 m0, s2
	v_readfirstlane_b32 s2, v4
	v_add_u32_e32 v4, 0x8000, v151
	s_waitcnt vmcnt(4)
	s_waitcnt lgkmcnt(0)
	s_barrier
	global_load_lds_dwordx4 v[2:3], off
	v_lshl_add_u64 v[2:3], v[66:67], 0, s[16:17]
	s_mov_b32 m0, s2
	v_readfirstlane_b32 s2, v4
	v_add_u32_e32 v4, 0xa000, v151
	global_load_lds_dwordx4 v[2:3], off
	v_lshl_add_u64 v[2:3], v[68:69], 0, s[12:13]
	s_mov_b32 m0, s2
	v_readfirstlane_b32 s2, v4
	global_load_lds_dwordx4 v[2:3], off
	v_lshl_add_u64 v[2:3], v[68:69], 0, s[16:17]
	s_mov_b32 m0, s2
	s_nop 0
	global_load_lds_dwordx4 v[2:3], off
	v_mov_b32_e32 v73, v152
	v_mov_b32_e32 v78, v141
	s_nop 0
	v_xad_u32 v6, v78, v142, v73
	v_xad_u32 v14, v78, v146, v73
	ds_read_b128 v[2:5], v6
	ds_read_b128 v[6:9], v6 offset:8192
	ds_read_b128 v[10:13], v14
	ds_read_b128 v[14:17], v14 offset:8192
	v_xad_u32 v18, v78, v143, v73
	ds_read_b128 v[50:53], v18
	ds_read_b128 v[54:57], v18 offset:8192
	v_xad_u32 v18, v78, v147, v73
	ds_read_b128 v[58:61], v18
	ds_read_b128 v[62:65], v18 offset:8192
	s_waitcnt lgkmcnt(0)
	v_mfma_f32_32x32x16_bf16 v[34:49], v[2:5], v[98:101], 0
	v_xad_u32 v74, v78, v148, v73
	v_mfma_f32_32x32x16_bf16 v[18:33], v[6:9], v[98:101], 0
	v_xad_u32 v6, v78, v144, v73
	ds_read_b128 v[2:5], v6
	ds_read_b128 v[6:9], v6 offset:8192
	v_mfma_f32_32x32x16_bf16 v[34:49], v[10:13], v[102:105], v[34:49]
	ds_read_b128 v[10:13], v74
	ds_read_b128 v[74:77], v74 offset:8192
	v_mfma_f32_32x32x16_bf16 v[18:33], v[14:17], v[102:105], v[18:33]
	v_mfma_f32_32x32x16_bf16 v[34:49], v[50:53], v[106:109], v[34:49]
	v_xad_u32 v50, v78, v145, v73
	ds_read_b128 v[14:17], v50
	ds_read_b128 v[50:53], v50 offset:8192
	v_mfma_f32_32x32x16_bf16 v[18:33], v[54:57], v[106:109], v[18:33]
	v_mfma_f32_32x32x16_bf16 v[34:49], v[58:61], v[110:113], v[34:49]
	v_xad_u32 v58, v78, v149, v73
	ds_read_b128 v[54:57], v58
	ds_read_b128 v[58:61], v58 offset:8192
	v_mfma_f32_32x32x16_bf16 v[18:33], v[62:65], v[110:113], v[18:33]
	s_waitcnt lgkmcnt(0)
	v_mfma_f32_32x32x16_bf16 v[34:49], v[2:5], v[114:117], v[34:49]
	v_mfma_f32_32x32x16_bf16 v[18:33], v[6:9], v[114:117], v[18:33]
	v_mfma_f32_32x32x16_bf16 v[34:49], v[10:13], v[118:121], v[34:49]
	v_mfma_f32_32x32x16_bf16 v[18:33], v[74:77], v[118:121], v[18:33]
	v_mfma_f32_32x32x16_bf16 v[34:49], v[14:17], v[122:125], v[34:49]
	v_mfma_f32_32x32x16_bf16 v[18:33], v[50:53], v[122:125], v[18:33]
	v_mfma_f32_32x32x16_bf16 v[34:49], v[54:57], v[126:129], v[34:49]
	v_mfma_f32_32x32x16_bf16 v[18:33], v[58:61], v[126:129], v[18:33]
	s_nop 10
	v_max_f32_e32 v2, v35, v35
	v_max_f32_e32 v3, v34, v34
	v_max_f32_e32 v2, v3, v2
	v_max3_f32 v2, v2, v36, v37
	v_max3_f32 v2, v2, v38, v39
	v_max3_f32 v2, v2, v40, v41
	v_max3_f32 v2, v2, v42, v43
	v_max3_f32 v2, v2, v44, v45
	v_max3_f32 v2, v2, v46, v47
	v_max3_f32 v2, v2, v48, v49
	v_max3_f32 v2, v2, v18, v19
	v_max3_f32 v2, v2, v20, v21
	v_max3_f32 v2, v2, v22, v23
	v_max3_f32 v2, v2, v24, v25
	v_max3_f32 v2, v2, v26, v27
	v_max3_f32 v2, v2, v28, v29
	v_max3_f32 v2, v2, v30, v31
	v_max3_f32 v2, v2, v32, v33
	v_mov_b32_e32 v3, v2
	s_nop 1
	v_permlane32_swap_b32_e32 v2, v3
	v_max_f32_e32 v3, v3, v3
	v_max_f32_e32 v2, v2, v2
	v_max_f32_e32 v2, v2, v3
	v_max_f32_e32 v50, 0xf149f2ca, v2
	v_add_f32_e32 v3, 0x7149f2ca, v2
	v_sub_f32_e32 v2, 0xf149f2ca, v50
	v_mul_f32_e32 v2, 0x3e0293ee, v2
	v_exp_f32_e32 v2, v2
	v_cmp_ge_f32_e32 vcc, s46, v3
	s_cmp_eq_u64 vcc, exec
	s_cselect_b64 s[2:3], -1, 0
	v_cndmask_b32_e64 v137, v2, 1.0, s[2:3]
	v_cmp_gt_f32_e32 vcc, 1.0, v137
	s_cbranch_vccz .LBB0_729
	s_and_saveexec_b64 s[26:27], s[0:1]
	ds_write_b32 v153, v137 offset:128
	s_or_b64 exec, exec, s[26:27]
	s_waitcnt lgkmcnt(0)
	ds_read_b128 v[2:5], v154 offset:224
	ds_read_b128 v[6:9], v154 offset:192
	ds_read_b128 v[52:55], v154 offset:160
	ds_read_b128 v[56:59], v154 offset:128
	s_waitcnt lgkmcnt(0)
	v_pk_mul_f32 v[16:17], v[4:5], 0 op_sel_hi:[1,0]
	v_pk_mul_f32 v[12:13], v[8:9], 0 op_sel_hi:[1,0]
	v_pk_mul_f32 v[8:9], v[54:55], 0 op_sel_hi:[1,0]
	v_pk_mul_f32 v[4:5], v[58:59], 0 op_sel_hi:[1,0]
	v_pk_mul_f32 v[14:15], v[2:3], 0 op_sel_hi:[1,0]
	v_pk_mul_f32 v[10:11], v[6:7], 0 op_sel_hi:[1,0]
	v_pk_mul_f32 v[6:7], v[52:53], 0 op_sel_hi:[1,0]
	v_pk_mul_f32 v[2:3], v[56:57], 0 op_sel_hi:[1,0]
	s_branch .LBB0_730

.LBB0_730:
	v_cndmask_b32_e64 v158, v50, v156, s[2:3]
	v_mul_f32_e32 v50, 0xbe0293ee, v158
	v_fmamk_f32 v34, v34, 0x3e0293ee, v50
	v_exp_f32_e32 v34, v34
	v_fmamk_f32 v35, v35, 0x3e0293ee, v50
	v_exp_f32_e32 v35, v35
	v_fmamk_f32 v36, v36, 0x3e0293ee, v50
	v_exp_f32_e32 v36, v36
	v_fmamk_f32 v37, v37, 0x3e0293ee, v50
	v_exp_f32_e32 v37, v37
	v_fmamk_f32 v38, v38, 0x3e0293ee, v50
	v_fmamk_f32 v39, v39, 0x3e0293ee, v50
	v_fmamk_f32 v40, v40, 0x3e0293ee, v50
	v_fmamk_f32 v41, v41, 0x3e0293ee, v50
	v_fmamk_f32 v42, v42, 0x3e0293ee, v50
	v_fmamk_f32 v43, v43, 0x3e0293ee, v50
	v_fmamk_f32 v44, v44, 0x3e0293ee, v50
	v_fmamk_f32 v45, v45, 0x3e0293ee, v50
	v_fmamk_f32 v46, v46, 0x3e0293ee, v50
	v_fmamk_f32 v47, v47, 0x3e0293ee, v50
	v_fmamk_f32 v48, v48, 0x3e0293ee, v50
	v_fmamk_f32 v49, v49, 0x3e0293ee, v50
	v_fmamk_f32 v18, v18, 0x3e0293ee, v50
	v_fmamk_f32 v19, v19, 0x3e0293ee, v50
	v_fmamk_f32 v20, v20, 0x3e0293ee, v50
	v_fmamk_f32 v21, v21, 0x3e0293ee, v50
	v_fmamk_f32 v22, v22, 0x3e0293ee, v50
	v_fmamk_f32 v23, v23, 0x3e0293ee, v50
	v_fmamk_f32 v24, v24, 0x3e0293ee, v50
	v_fmamk_f32 v25, v25, 0x3e0293ee, v50
	v_fmamk_f32 v26, v26, 0x3e0293ee, v50
	v_fmamk_f32 v27, v27, 0x3e0293ee, v50
	v_fmamk_f32 v28, v28, 0x3e0293ee, v50
	v_fmamk_f32 v29, v29, 0x3e0293ee, v50
	v_fmamk_f32 v30, v30, 0x3e0293ee, v50
	v_fmamk_f32 v31, v31, 0x3e0293ee, v50
	v_fmamk_f32 v32, v32, 0x3e0293ee, v50
	v_fmac_f32_e32 v50, 0x3e0293ee, v33
	v_exp_f32_e32 v38, v38
	v_exp_f32_e32 v33, v50
	v_add_f32_e32 v50, 0, v34
	v_exp_f32_e32 v39, v39
	v_add_f32_e32 v50, v35, v50
	v_exp_f32_e32 v40, v40
	v_add_f32_e32 v50, v36, v50
	v_exp_f32_e32 v41, v41
	v_add_f32_e32 v50, v37, v50
	v_exp_f32_e32 v42, v42
	v_add_f32_e32 v50, v38, v50
	v_exp_f32_e32 v43, v43
	v_add_f32_e32 v50, v39, v50
	v_exp_f32_e32 v44, v44
	v_add_f32_e32 v50, v40, v50
	v_exp_f32_e32 v45, v45
	v_add_f32_e32 v50, v41, v50
	v_exp_f32_e32 v46, v46
	v_add_f32_e32 v50, v42, v50
	v_exp_f32_e32 v47, v47
	v_add_f32_e32 v50, v43, v50
	v_exp_f32_e32 v48, v48
	v_add_f32_e32 v50, v44, v50
	v_exp_f32_e32 v49, v49
	v_add_f32_e32 v50, v45, v50
	v_exp_f32_e32 v18, v18
	v_add_f32_e32 v50, v46, v50
	v_exp_f32_e32 v19, v19
	v_add_f32_e32 v50, v47, v50
	v_exp_f32_e32 v20, v20
	v_add_f32_e32 v50, v48, v50
	v_exp_f32_e32 v21, v21
	v_add_f32_e32 v50, v49, v50
	v_exp_f32_e32 v22, v22
	v_add_f32_e32 v50, v18, v50
	v_exp_f32_e32 v23, v23
	v_add_f32_e32 v50, v19, v50
	v_exp_f32_e32 v24, v24
	v_add_f32_e32 v50, v20, v50
	v_exp_f32_e32 v25, v25
	v_add_f32_e32 v50, v21, v50
	v_exp_f32_e32 v26, v26
	v_add_f32_e32 v50, v22, v50
	v_exp_f32_e32 v27, v27
	v_add_f32_e32 v50, v23, v50
	v_exp_f32_e32 v28, v28
	v_add_f32_e32 v50, v24, v50
	v_exp_f32_e32 v29, v29
	v_add_f32_e32 v50, v25, v50
	v_exp_f32_e32 v30, v30
	v_add_f32_e32 v50, v26, v50
	v_exp_f32_e32 v31, v31
	v_add_f32_e32 v50, v27, v50
	v_exp_f32_e32 v32, v32
	v_add_f32_e32 v50, v28, v50
	v_add_f32_e32 v50, v29, v50
	v_add_f32_e32 v50, v30, v50
	v_add_f32_e32 v50, v31, v50
	v_add_f32_e32 v50, v32, v50
	v_add_f32_e32 v159, v33, v50
	v_mov_b32_e32 v160, v159
	v_cvt_pk_bf16_f32 v74, v34, v35
	v_cvt_pk_bf16_f32 v75, v36, v37
	v_cvt_pk_bf16_f32 v76, v38, v39
	v_cvt_pk_bf16_f32 v77, v40, v41
	v_cvt_pk_bf16_f32 v78, v42, v43
	v_cvt_pk_bf16_f32 v79, v44, v45
	v_cvt_pk_bf16_f32 v80, v46, v47
	v_cvt_pk_bf16_f32 v81, v48, v49
	v_cvt_pk_bf16_f32 v82, v18, v19
	v_cvt_pk_bf16_f32 v83, v20, v21
	v_cvt_pk_bf16_f32 v84, v22, v23
	v_cvt_pk_bf16_f32 v85, v24, v25
	v_cvt_pk_bf16_f32 v86, v26, v27
	v_cvt_pk_bf16_f32 v87, v28, v29
	v_cvt_pk_bf16_f32 v88, v30, v31
	v_cvt_pk_bf16_f32 v89, v32, v33
	s_lshl_b64 s[24:25], s[24:25], 11
	s_lshl_b32 s51, s28, 7
	v_permlane32_swap_b32_e32 v159, v160
	v_permlane32_swap_b32_e32 v74, v76
	v_permlane32_swap_b32_e32 v75, v77
	v_permlane32_swap_b32_e32 v78, v80
	v_permlane32_swap_b32_e32 v79, v81
	v_permlane32_swap_b32_e32 v82, v84
	v_permlane32_swap_b32_e32 v83, v85
	v_permlane32_swap_b32_e32 v86, v88
	v_permlane32_swap_b32_e32 v87, v89
	ds_read_b64_tr_b16 v[34:35], v138 offset:0
	ds_read_b64_tr_b16 v[36:37], v138 offset:0x800
	ds_read_b64_tr_b16 v[38:39], v138 offset:0x1000
	ds_read_b64_tr_b16 v[40:41], v138 offset:0x1800
	ds_read_b64_tr_b16 v[42:43], v138 offset:0x2000
	ds_read_b64_tr_b16 v[44:45], v138 offset:0x2800
	ds_read_b64_tr_b16 v[46:47], v138 offset:0x3000
	ds_read_b64_tr_b16 v[48:49], v138 offset:0x3800
	ds_read_b64_tr_b16 v[50:51], v138 offset:0x200
	ds_read_b64_tr_b16 v[52:53], v138 offset:0xa00
	ds_read_b64_tr_b16 v[54:55], v138 offset:0x1200
	ds_read_b64_tr_b16 v[56:57], v138 offset:0x1a00
	ds_read_b64_tr_b16 v[58:59], v138 offset:0x2200
	ds_read_b64_tr_b16 v[60:61], v138 offset:0x2a00
	ds_read_b64_tr_b16 v[62:63], v138 offset:0x3200
	ds_read_b64_tr_b16 v[64:65], v138 offset:0x3a00
	s_waitcnt lgkmcnt(8)
	s_nop 0
	v_mfma_f32_32x32x16_bf16 v[18:33], v[74:77], v[34:37], v[2:17]
	v_mfma_f32_32x32x16_bf16 v[18:33], v[78:81], v[38:41], v[18:33]
	v_mfma_f32_32x32x16_bf16 v[18:33], v[82:85], v[42:45], v[18:33]
	v_mfma_f32_32x32x16_bf16 v[18:33], v[86:89], v[46:49], v[18:33]
	ds_read_b64_tr_b16 v[90:91], v138 offset:0x400
	ds_read_b64_tr_b16 v[92:93], v138 offset:0xc00
	ds_read_b64_tr_b16 v[94:95], v138 offset:0x1400
	ds_read_b64_tr_b16 v[96:97], v138 offset:0x1c00
	ds_read_b64_tr_b16 v[162:163], v138 offset:0x2400
	ds_read_b64_tr_b16 v[164:165], v138 offset:0x2c00
	ds_read_b64_tr_b16 v[166:167], v138 offset:0x3400
	ds_read_b64_tr_b16 v[168:169], v138 offset:0x3c00
	s_waitcnt lgkmcnt(8)
	v_mfma_f32_32x32x16_bf16 v[34:49], v[74:77], v[50:53], v[2:17]
	v_mfma_f32_32x32x16_bf16 v[34:49], v[78:81], v[54:57], v[34:49]
	v_mfma_f32_32x32x16_bf16 v[34:49], v[82:85], v[58:61], v[34:49]
	v_mfma_f32_32x32x16_bf16 v[34:49], v[86:89], v[62:65], v[34:49]
	ds_read_b64_tr_b16 v[170:171], v138 offset:0x600
	ds_read_b64_tr_b16 v[172:173], v138 offset:0xe00
	ds_read_b64_tr_b16 v[174:175], v138 offset:0x1600
	ds_read_b64_tr_b16 v[176:177], v138 offset:0x1e00
	ds_read_b64_tr_b16 v[178:179], v138 offset:0x2600
	ds_read_b64_tr_b16 v[180:181], v138 offset:0x2e00
	ds_read_b64_tr_b16 v[182:183], v138 offset:0x3600
	ds_read_b64_tr_b16 v[184:185], v138 offset:0x3e00
	s_waitcnt lgkmcnt(8)
	v_mfma_f32_32x32x16_bf16 v[50:65], v[74:77], v[90:93], v[2:17]
	v_mfma_f32_32x32x16_bf16 v[50:65], v[78:81], v[94:97], v[50:65]
	v_mfma_f32_32x32x16_bf16 v[50:65], v[82:85], v[162:165], v[50:65]
	v_mfma_f32_32x32x16_bf16 v[50:65], v[86:89], v[166:169], v[50:65]
	s_waitcnt lgkmcnt(0)
	v_mfma_f32_32x32x16_bf16 v[2:17], v[74:77], v[170:173], v[2:17]
	v_mfma_f32_32x32x16_bf16 v[2:17], v[78:81], v[174:177], v[2:17]
	v_mfma_f32_32x32x16_bf16 v[2:17], v[82:85], v[178:181], v[2:17]
	v_mfma_f32_32x32x16_bf16 v[2:17], v[86:89], v[182:185], v[2:17]
	v_readfirstlane_b32 s2, v70
	v_lshl_add_u64 v[74:75], v[66:67], 0, s[20:21]
	s_mov_b32 m0, s2
	v_readfirstlane_b32 s2, v71
	s_waitcnt vmcnt(4)
	s_nop 0
	s_barrier
	global_load_lds_dwordx4 v[74:75], off
	v_lshl_add_u64 v[66:67], v[66:67], 0, s[22:23]
	s_mov_b32 m0, s2
	v_readfirstlane_b32 s2, v151
	global_load_lds_dwordx4 v[66:67], off
	v_lshl_add_u64 v[66:67], v[68:69], 0, s[20:21]
	s_mov_b32 m0, s2
	v_readfirstlane_b32 s2, v72
	global_load_lds_dwordx4 v[66:67], off
	v_lshl_add_u64 v[66:67], v[68:69], 0, s[22:23]
	s_mov_b32 m0, s2
	s_nop 0
	global_load_lds_dwordx4 v[66:67], off
	v_mov_b32_e32 v161, v139
	v_mov_b32_e32 v198, v141
	s_nop 0
	v_xad_u32 v70, v198, v142, v161
	v_xad_u32 v74, v198, v146, v161
	ds_read_b128 v[66:69], v70
	ds_read_b128 v[70:73], v70 offset:8192
	ds_read_b128 v[162:165], v74
	ds_read_b128 v[166:169], v74 offset:8192
	v_xad_u32 v74, v198, v143, v161
	ds_read_b128 v[170:173], v74
	ds_read_b128 v[174:177], v74 offset:8192
	v_xad_u32 v74, v198, v147, v161
	ds_read_b128 v[178:181], v74
	ds_read_b128 v[182:185], v74 offset:8192
	s_waitcnt lgkmcnt(0)
	v_mfma_f32_32x32x16_bf16 v[82:97], v[66:69], v[98:101], 0
	v_xad_u32 v186, v198, v144, v161
	v_xad_u32 v194, v198, v148, v161
	v_mfma_f32_32x32x16_bf16 v[66:81], v[70:73], v[98:101], 0
	v_mfma_f32_32x32x16_bf16 v[82:97], v[162:165], v[102:105], v[82:97]
	ds_read_b128 v[162:165], v186
	ds_read_b128 v[186:189], v186 offset:8192
	ds_read_b128 v[190:193], v194
	ds_read_b128 v[194:197], v194 offset:8192
	v_mfma_f32_32x32x16_bf16 v[66:81], v[166:169], v[102:105], v[66:81]
	v_mfma_f32_32x32x16_bf16 v[82:97], v[170:173], v[106:109], v[82:97]
	v_xad_u32 v170, v198, v145, v161
	v_xad_u32 v161, v198, v149, v161
	ds_read_b128 v[166:169], v170
	ds_read_b128 v[170:173], v170 offset:8192
	v_mfma_f32_32x32x16_bf16 v[66:81], v[174:177], v[106:109], v[66:81]
	v_mfma_f32_32x32x16_bf16 v[82:97], v[178:181], v[110:113], v[82:97]
	ds_read_b128 v[174:177], v161
	ds_read_b128 v[178:181], v161 offset:8192
	v_mfma_f32_32x32x16_bf16 v[66:81], v[182:185], v[110:113], v[66:81]
	s_waitcnt lgkmcnt(0)
	v_mfma_f32_32x32x16_bf16 v[82:97], v[162:165], v[114:117], v[82:97]
	v_mfma_f32_32x32x16_bf16 v[66:81], v[186:189], v[114:117], v[66:81]
	v_mfma_f32_32x32x16_bf16 v[82:97], v[190:193], v[118:121], v[82:97]
	v_mfma_f32_32x32x16_bf16 v[66:81], v[194:197], v[118:121], v[66:81]
	v_mfma_f32_32x32x16_bf16 v[82:97], v[166:169], v[122:125], v[82:97]
	v_mfma_f32_32x32x16_bf16 v[66:81], v[170:173], v[122:125], v[66:81]
	v_mfma_f32_32x32x16_bf16 v[82:97], v[174:177], v[126:129], v[82:97]
	v_mfma_f32_32x32x16_bf16 v[66:81], v[178:181], v[126:129], v[66:81]
	s_nop 10
	v_max_f32_e32 v161, v83, v83
	v_max_f32_e32 v162, v82, v82
	v_max_f32_e32 v161, v162, v161
	v_max3_f32 v161, v161, v84, v85
	v_max3_f32 v161, v161, v86, v87
	v_max3_f32 v161, v161, v88, v89
	v_max3_f32 v161, v161, v90, v91
	v_max3_f32 v161, v161, v92, v93
	v_max3_f32 v161, v161, v94, v95
	v_max3_f32 v161, v161, v96, v97
	v_max3_f32 v161, v161, v66, v67
	v_max3_f32 v161, v161, v68, v69
	v_max3_f32 v161, v161, v70, v71
	v_max3_f32 v161, v161, v72, v73
	v_max3_f32 v161, v161, v74, v75
	v_max3_f32 v161, v161, v76, v77
	v_max3_f32 v161, v161, v78, v79
	v_max3_f32 v161, v161, v80, v81
	v_mov_b32_e32 v162, v161
	s_nop 1
	v_permlane32_swap_b32_e32 v161, v162
	v_max_f32_e32 v162, v162, v162
	v_max_f32_e32 v161, v161, v161
	v_max_f32_e32 v161, v161, v162
	v_max_f32_e32 v162, v158, v158
	v_max_f32_e32 v162, v162, v161
	v_sub_f32_e32 v163, v161, v158
	v_sub_f32_e32 v161, v158, v162
	v_mul_f32_e32 v161, 0x3e0293ee, v161
	v_exp_f32_e32 v161, v161
	v_cmp_ge_f32_e32 vcc, s46, v163
	s_cmp_eq_u64 vcc, exec
	s_cselect_b64 s[2:3], -1, 0
	v_cndmask_b32_e64 v161, v161, 1.0, s[2:3]
	v_cmp_gt_f32_e32 vcc, 1.0, v161
	s_cbranch_vccz .LBB0_734
	s_and_saveexec_b64 s[26:27], s[0:1]
	ds_write_b32 v153, v161 offset:128
	s_or_b64 exec, exec, s[26:27]
	s_waitcnt lgkmcnt(0)
	ds_read_b128 v[164:167], v154 offset:224
	ds_read_b128 v[168:171], v154 offset:192
	ds_read_b128 v[172:175], v154 offset:160
	ds_read_b128 v[176:179], v154 offset:128
	s_waitcnt lgkmcnt(0)
	v_pk_mul_f32 v[32:33], v[32:33], v[166:167]
	v_pk_mul_f32 v[28:29], v[28:29], v[170:171]
	v_pk_mul_f32 v[24:25], v[24:25], v[174:175]
	v_pk_mul_f32 v[20:21], v[20:21], v[178:179]
	v_pk_mul_f32 v[30:31], v[30:31], v[164:165]
	v_pk_mul_f32 v[26:27], v[26:27], v[168:169]
	v_pk_mul_f32 v[22:23], v[22:23], v[172:173]
	v_pk_mul_f32 v[18:19], v[18:19], v[176:177]
	v_pk_mul_f32 v[48:49], v[48:49], v[166:167]
	v_pk_mul_f32 v[44:45], v[44:45], v[170:171]
	v_pk_mul_f32 v[40:41], v[40:41], v[174:175]
	v_pk_mul_f32 v[36:37], v[36:37], v[178:179]
	v_pk_mul_f32 v[46:47], v[46:47], v[164:165]
	v_pk_mul_f32 v[42:43], v[42:43], v[168:169]
	v_pk_mul_f32 v[38:39], v[38:39], v[172:173]
	v_pk_mul_f32 v[34:35], v[34:35], v[176:177]
	v_pk_mul_f32 v[64:65], v[64:65], v[166:167]
	v_pk_mul_f32 v[60:61], v[60:61], v[170:171]
	v_pk_mul_f32 v[56:57], v[56:57], v[174:175]
	v_pk_mul_f32 v[52:53], v[52:53], v[178:179]
	v_pk_mul_f32 v[62:63], v[62:63], v[164:165]
	v_pk_mul_f32 v[58:59], v[58:59], v[168:169]
	v_pk_mul_f32 v[54:55], v[54:55], v[172:173]
	v_pk_mul_f32 v[50:51], v[50:51], v[176:177]
	v_pk_mul_f32 v[16:17], v[16:17], v[166:167]
	v_pk_mul_f32 v[12:13], v[12:13], v[170:171]
	v_pk_mul_f32 v[8:9], v[8:9], v[174:175]
	v_pk_mul_f32 v[4:5], v[4:5], v[178:179]
	v_pk_mul_f32 v[14:15], v[14:15], v[164:165]
	v_pk_mul_f32 v[10:11], v[10:11], v[168:169]
	v_pk_mul_f32 v[6:7], v[6:7], v[172:173]
	v_pk_mul_f32 v[2:3], v[2:3], v[176:177]

.LBB0_739:
	s_lshl_b32 s55, s54, 14
	s_nop 0
	s_barrier
	v_add_u32_e32 v159, s55, v152
	v_mov_b32_e32 v196, v141
	s_nop 0
	v_xad_u32 v70, v196, v142, v159
	v_xad_u32 v74, v196, v146, v159
	ds_read_b128 v[66:69], v70
	ds_read_b128 v[70:73], v70 offset:8192
	ds_read_b128 v[160:163], v74
	ds_read_b128 v[164:167], v74 offset:8192
	v_xad_u32 v74, v196, v143, v159
	ds_read_b128 v[168:171], v74
	ds_read_b128 v[172:175], v74 offset:8192
	v_xad_u32 v74, v196, v147, v159
	ds_read_b128 v[176:179], v74
	ds_read_b128 v[180:183], v74 offset:8192
	s_waitcnt lgkmcnt(7)
	v_mfma_f32_32x32x16_bf16 v[82:97], v[66:69], v[98:101], 0
	v_xad_u32 v184, v196, v144, v159
	v_xad_u32 v192, v196, v148, v159
	s_waitcnt lgkmcnt(6)
	v_mfma_f32_32x32x16_bf16 v[66:81], v[70:73], v[98:101], 0
	s_waitcnt lgkmcnt(5)
	v_mfma_f32_32x32x16_bf16 v[82:97], v[160:163], v[102:105], v[82:97]
	ds_read_b128 v[160:163], v184
	ds_read_b128 v[184:187], v184 offset:8192
	ds_read_b128 v[188:191], v192
	ds_read_b128 v[192:195], v192 offset:8192
	s_waitcnt lgkmcnt(8)
	v_mfma_f32_32x32x16_bf16 v[66:81], v[164:167], v[102:105], v[66:81]
	s_waitcnt lgkmcnt(7)
	v_mfma_f32_32x32x16_bf16 v[82:97], v[168:171], v[106:109], v[82:97]
	v_xad_u32 v168, v196, v145, v159
	v_xad_u32 v159, v196, v149, v159
	ds_read_b128 v[164:167], v168
	ds_read_b128 v[168:171], v168 offset:8192
	s_waitcnt lgkmcnt(8)
	v_mfma_f32_32x32x16_bf16 v[66:81], v[172:175], v[106:109], v[66:81]
	s_waitcnt lgkmcnt(7)
	v_mfma_f32_32x32x16_bf16 v[82:97], v[176:179], v[110:113], v[82:97]
	ds_read_b128 v[172:175], v159
	ds_read_b128 v[176:179], v159 offset:8192
	s_waitcnt lgkmcnt(8)
	v_mfma_f32_32x32x16_bf16 v[66:81], v[180:183], v[110:113], v[66:81]
	s_waitcnt lgkmcnt(7)
	v_mfma_f32_32x32x16_bf16 v[82:97], v[160:163], v[114:117], v[82:97]
	s_waitcnt lgkmcnt(6)
	v_mfma_f32_32x32x16_bf16 v[66:81], v[184:187], v[114:117], v[66:81]
	s_waitcnt lgkmcnt(5)
	v_mfma_f32_32x32x16_bf16 v[82:97], v[188:191], v[118:121], v[82:97]
	s_waitcnt lgkmcnt(4)
	v_mfma_f32_32x32x16_bf16 v[66:81], v[192:195], v[118:121], v[66:81]
	s_waitcnt lgkmcnt(3)
	v_mfma_f32_32x32x16_bf16 v[82:97], v[164:167], v[122:125], v[82:97]
	s_waitcnt lgkmcnt(2)
	v_mfma_f32_32x32x16_bf16 v[66:81], v[168:171], v[122:125], v[66:81]
	s_waitcnt lgkmcnt(1)
	v_mfma_f32_32x32x16_bf16 v[82:97], v[172:175], v[126:129], v[82:97]
	s_waitcnt lgkmcnt(0)
	v_mfma_f32_32x32x16_bf16 v[66:81], v[176:179], v[126:129], v[66:81]
	s_nop 9
	v_max_f32_e32 v159, v83, v83
	v_max_f32_e32 v160, v82, v82
	v_max_f32_e32 v159, v160, v159
	v_max3_f32 v159, v159, v84, v85
	v_max3_f32 v159, v159, v86, v87
	v_max3_f32 v159, v159, v88, v89
	v_max3_f32 v159, v159, v90, v91
	v_max3_f32 v159, v159, v92, v93
	v_max3_f32 v159, v159, v94, v95
	v_max3_f32 v159, v159, v96, v97
	v_max3_f32 v159, v159, v66, v67
	v_max3_f32 v159, v159, v68, v69
	v_max3_f32 v159, v159, v70, v71
	v_max3_f32 v159, v159, v72, v73
	v_max3_f32 v159, v159, v74, v75
	v_max3_f32 v159, v159, v76, v77
	v_max3_f32 v159, v159, v78, v79
	v_max3_f32 v159, v159, v80, v81
	v_mov_b32_e32 v160, v159
	s_nop 1
	v_permlane32_swap_b32_e32 v159, v160
	v_max_f32_e32 v160, v160, v160
	v_max_f32_e32 v159, v159, v159
	v_max_f32_e32 v159, v159, v160
	v_max_f32_e32 v161, v137, v137
	v_sub_f32_e32 v160, v159, v137
	v_max_f32_e32 v159, v161, v159
	v_sub_f32_e32 v161, v137, v159
	v_mul_f32_e32 v161, 0x3e0293ee, v161
	v_exp_f32_e32 v161, v161
	v_cmp_ge_f32_e32 vcc, s46, v160
	s_cmp_eq_u64 vcc, exec
	s_cselect_b64 s[2:3], -1, 0
	v_cndmask_b32_e64 v160, v161, 1.0, s[2:3]
	v_cmp_gt_f32_e32 vcc, 1.0, v160
	s_cbranch_vccz .LBB0_743
	s_and_saveexec_b64 s[28:29], s[0:1]
	ds_write_b32 v153, v160 offset:128
	s_or_b64 exec, exec, s[28:29]
	s_waitcnt lgkmcnt(0)
	ds_read_b128 v[162:165], v154 offset:224
	ds_read_b128 v[166:169], v154 offset:192
	ds_read_b128 v[170:173], v154 offset:160
	ds_read_b128 v[174:177], v154 offset:128
	s_waitcnt lgkmcnt(3)
	v_pk_mul_f32 v[32:33], v[32:33], v[164:165]
	s_waitcnt lgkmcnt(2)
	v_pk_mul_f32 v[28:29], v[28:29], v[168:169]
	s_waitcnt lgkmcnt(1)
	v_pk_mul_f32 v[24:25], v[24:25], v[172:173]
	s_waitcnt lgkmcnt(0)
	v_pk_mul_f32 v[20:21], v[20:21], v[176:177]
	v_pk_mul_f32 v[30:31], v[30:31], v[162:163]
	v_pk_mul_f32 v[26:27], v[26:27], v[166:167]
	v_pk_mul_f32 v[22:23], v[22:23], v[170:171]
	v_pk_mul_f32 v[18:19], v[18:19], v[174:175]
	v_pk_mul_f32 v[48:49], v[48:49], v[164:165]
	v_pk_mul_f32 v[44:45], v[44:45], v[168:169]
	v_pk_mul_f32 v[40:41], v[40:41], v[172:173]
	v_pk_mul_f32 v[36:37], v[36:37], v[176:177]
	v_pk_mul_f32 v[46:47], v[46:47], v[162:163]
	v_pk_mul_f32 v[42:43], v[42:43], v[166:167]
	v_pk_mul_f32 v[38:39], v[38:39], v[170:171]
	v_pk_mul_f32 v[34:35], v[34:35], v[174:175]
	v_pk_mul_f32 v[64:65], v[64:65], v[164:165]
	v_pk_mul_f32 v[60:61], v[60:61], v[168:169]
	v_pk_mul_f32 v[56:57], v[56:57], v[172:173]
	v_pk_mul_f32 v[52:53], v[52:53], v[176:177]
	v_pk_mul_f32 v[62:63], v[62:63], v[162:163]
	v_pk_mul_f32 v[58:59], v[58:59], v[166:167]
	v_pk_mul_f32 v[54:55], v[54:55], v[170:171]
	v_pk_mul_f32 v[50:51], v[50:51], v[174:175]
	v_pk_mul_f32 v[16:17], v[16:17], v[164:165]
	v_pk_mul_f32 v[12:13], v[12:13], v[168:169]
	v_pk_mul_f32 v[8:9], v[8:9], v[172:173]
	v_pk_mul_f32 v[4:5], v[4:5], v[176:177]
	v_pk_mul_f32 v[14:15], v[14:15], v[162:163]
	v_pk_mul_f32 v[10:11], v[10:11], v[166:167]
	v_pk_mul_f32 v[6:7], v[6:7], v[170:171]
	v_pk_mul_f32 v[2:3], v[2:3], v[174:175]

.LBB0_3428:
	s_add_i32 s19, s18, 2
	s_cmp_lt_i32 s19, s51
	s_mov_b64 s[2:3], -1
	s_waitcnt lgkmcnt(0)
	s_barrier
	s_cbranch_scc1 .LBB0_3430
	s_lshl_b32 s56, s54, 14
	s_mov_b64 s[2:3], 0

.LBB0_3443:
	s_and_b32 s24, s42, 15
	s_lshl_b32 s2, s24, 2
	v_mov_b32_e32 v2, s2
	s_lshl_b32 s2, s42, 4
	s_and_b32 s20, s2, 0xffffff00
	s_ashr_i32 s21, s20, 31
	s_lshl_b64 s[2:3], s[20:21], 12
	s_add_u32 s2, s26, s2
	s_addc_u32 s3, s27, s3
	s_lshl_b32 s22, s24, 8
	s_add_u32 s2, s2, s22
	s_addc_u32 s3, s3, 0
	s_lshl_b32 s25, s42, 6
	s_lshl_b64 s[22:23], s[20:21], 10
	s_and_b32 s25, s25, 0x300
	s_or_b32 s22, s22, s25
	s_add_u32 s44, s28, s22
	v_add_u32_e32 v70, 0xc000, v151
	global_load_dword v157, v2, s[52:53] offset:64
	s_addc_u32 s45, s29, s23
	v_lshl_add_u64 v[2:3], s[2:3], 0, v[130:131]
	v_mov_b32_e32 v137, v131
	v_readfirstlane_b32 s2, v70
	v_add_u32_e32 v71, 0xe000, v151
	s_add_u32 s22, s30, s22
	v_lshl_add_u64 v[2:3], v[2:3], 0, v[136:137]
	v_lshl_add_u64 v[66:67], s[44:45], 0, v[132:133]
	s_mov_b32 m0, s2
	v_readfirstlane_b32 s2, v71
	s_addc_u32 s23, s31, s23
	global_load_dwordx4 v[98:101], v[2:3], off
	global_load_dwordx4 v[102:105], v[2:3], off offset:32
	global_load_dwordx4 v[106:109], v[2:3], off offset:64
	global_load_dwordx4 v[110:113], v[2:3], off offset:96
	global_load_dwordx4 v[114:117], v[2:3], off offset:128
	global_load_dwordx4 v[118:121], v[2:3], off offset:160
	global_load_dwordx4 v[122:125], v[2:3], off offset:192
	global_load_dwordx4 v[126:129], v[2:3], off offset:224
	v_lshl_add_u64 v[2:3], v[66:67], 0, s[6:7]
	global_load_lds_dwordx4 v[66:67], off
	s_mov_b32 m0, s2
	v_readfirstlane_b32 s2, v151
	v_add_u32_e32 v72, 0x2000, v151
	global_load_lds_dwordx4 v[2:3], off
	v_lshl_add_u64 v[68:69], s[22:23], 0, v[134:135]
	s_mov_b32 m0, s2
	v_readfirstlane_b32 s2, v72
	v_add_u32_e32 v4, s36, v140
	global_load_lds_dwordx4 v[68:69], off
	v_lshl_add_u64 v[2:3], v[68:69], 0, s[6:7]
	s_mov_b32 m0, s2
	v_readfirstlane_b32 s2, v4
	v_add_u32_e32 v4, s37, v140
	global_load_lds_dwordx4 v[2:3], off
	v_lshl_add_u64 v[2:3], v[66:67], 0, s[8:9]
	s_mov_b32 m0, s2
	v_readfirstlane_b32 s2, v4
	v_add_u32_e32 v4, 0x4000, v151
	global_load_lds_dwordx4 v[2:3], off
	v_lshl_add_u64 v[2:3], v[66:67], 0, s[10:11]
	s_mov_b32 m0, s2
	v_readfirstlane_b32 s2, v4
	v_add_u32_e32 v4, 0x6000, v151
	global_load_lds_dwordx4 v[2:3], off
	v_lshl_add_u64 v[2:3], v[68:69], 0, s[8:9]
	s_mov_b32 m0, s2
	v_readfirstlane_b32 s2, v4
	v_add_u32_e32 v4, s38, v140
	global_load_lds_dwordx4 v[2:3], off
	v_lshl_add_u64 v[2:3], v[68:69], 0, s[10:11]
	s_mov_b32 m0, s2
	v_readfirstlane_b32 s2, v4
	v_add_u32_e32 v4, s39, v140
	global_load_lds_dwordx4 v[2:3], off
	v_lshl_add_u64 v[2:3], v[66:67], 0, s[12:13]
	s_mov_b32 m0, s2
	v_readfirstlane_b32 s2, v4
	v_add_u32_e32 v4, 0x8000, v151
	s_waitcnt vmcnt(4)
	s_waitcnt lgkmcnt(0)
	s_barrier
	global_load_lds_dwordx4 v[2:3], off
	v_lshl_add_u64 v[2:3], v[66:67], 0, s[14:15]
	s_mov_b32 m0, s2
	v_readfirstlane_b32 s2, v4
	v_add_u32_e32 v4, 0xa000, v151
	global_load_lds_dwordx4 v[2:3], off
	v_lshl_add_u64 v[2:3], v[68:69], 0, s[12:13]
	s_mov_b32 m0, s2
	v_readfirstlane_b32 s2, v4
	global_load_lds_dwordx4 v[2:3], off
	v_lshl_add_u64 v[2:3], v[68:69], 0, s[14:15]
	s_mov_b32 m0, s2
	s_nop 0
	global_load_lds_dwordx4 v[2:3], off
	v_mov_b32_e32 v73, v141
	v_mov_b32_e32 v78, v152
	s_nop 0
	v_xad_u32 v6, v73, v142, v78
	v_xad_u32 v14, v73, v146, v78
	ds_read_b128 v[2:5], v6
	ds_read_b128 v[6:9], v6 offset:8192
	ds_read_b128 v[10:13], v14
	ds_read_b128 v[14:17], v14 offset:8192
	v_xad_u32 v18, v73, v143, v78
	ds_read_b128 v[50:53], v18
	ds_read_b128 v[54:57], v18 offset:8192
	v_xad_u32 v18, v73, v147, v78
	ds_read_b128 v[58:61], v18
	ds_read_b128 v[62:65], v18 offset:8192
	s_waitcnt lgkmcnt(0)
	v_mfma_f32_32x32x16_bf16 v[34:49], v[2:5], v[98:101], 0
	v_xad_u32 v74, v73, v148, v78
	v_mfma_f32_32x32x16_bf16 v[18:33], v[6:9], v[98:101], 0
	v_xad_u32 v6, v73, v144, v78
	ds_read_b128 v[2:5], v6
	ds_read_b128 v[6:9], v6 offset:8192
	v_mfma_f32_32x32x16_bf16 v[34:49], v[10:13], v[102:105], v[34:49]
	ds_read_b128 v[10:13], v74
	ds_read_b128 v[74:77], v74 offset:8192
	v_mfma_f32_32x32x16_bf16 v[18:33], v[14:17], v[102:105], v[18:33]
	v_mfma_f32_32x32x16_bf16 v[34:49], v[50:53], v[106:109], v[34:49]
	v_xad_u32 v50, v73, v145, v78
	ds_read_b128 v[14:17], v50
	ds_read_b128 v[50:53], v50 offset:8192
	v_mfma_f32_32x32x16_bf16 v[18:33], v[54:57], v[106:109], v[18:33]
	v_mfma_f32_32x32x16_bf16 v[34:49], v[58:61], v[110:113], v[34:49]
	v_xad_u32 v58, v73, v149, v78
	ds_read_b128 v[54:57], v58
	ds_read_b128 v[58:61], v58 offset:8192
	v_mfma_f32_32x32x16_bf16 v[18:33], v[62:65], v[110:113], v[18:33]
	s_waitcnt lgkmcnt(0)
	v_mfma_f32_32x32x16_bf16 v[34:49], v[2:5], v[114:117], v[34:49]
	v_mfma_f32_32x32x16_bf16 v[18:33], v[6:9], v[114:117], v[18:33]
	v_mfma_f32_32x32x16_bf16 v[34:49], v[10:13], v[118:121], v[34:49]
	v_mfma_f32_32x32x16_bf16 v[18:33], v[74:77], v[118:121], v[18:33]
	v_mfma_f32_32x32x16_bf16 v[34:49], v[14:17], v[122:125], v[34:49]
	v_mfma_f32_32x32x16_bf16 v[18:33], v[50:53], v[122:125], v[18:33]
	v_mfma_f32_32x32x16_bf16 v[34:49], v[54:57], v[126:129], v[34:49]
	v_mfma_f32_32x32x16_bf16 v[18:33], v[58:61], v[126:129], v[18:33]
	s_nop 10
	v_max_f32_e32 v2, v35, v35
	v_max_f32_e32 v3, v34, v34
	v_max_f32_e32 v2, v3, v2
	v_max3_f32 v2, v2, v36, v37
	v_max3_f32 v2, v2, v38, v39
	v_max3_f32 v2, v2, v40, v41
	v_max3_f32 v2, v2, v42, v43
	v_max3_f32 v2, v2, v44, v45
	v_max3_f32 v2, v2, v46, v47
	v_max3_f32 v2, v2, v48, v49
	v_max3_f32 v2, v2, v18, v19
	v_max3_f32 v2, v2, v20, v21
	v_max3_f32 v2, v2, v22, v23
	v_max3_f32 v2, v2, v24, v25
	v_max3_f32 v2, v2, v26, v27
	v_max3_f32 v2, v2, v28, v29
	v_max3_f32 v2, v2, v30, v31
	v_max3_f32 v2, v2, v32, v33
	v_mov_b32_e32 v3, v2
	s_nop 1
	v_permlane32_swap_b32_e32 v2, v3
	v_max_f32_e32 v3, v3, v3
	v_max_f32_e32 v2, v2, v2
	v_max_f32_e32 v2, v2, v3
	v_max_f32_e32 v50, 0xf149f2ca, v2
	v_add_f32_e32 v3, 0x7149f2ca, v2
	v_sub_f32_e32 v2, 0xf149f2ca, v50
	v_mul_f32_e32 v2, 0x3e0293ee, v2
	v_exp_f32_e32 v2, v2
	v_cmp_ge_f32_e32 vcc, s40, v3
	s_cmp_eq_u64 vcc, exec
	s_cselect_b64 s[2:3], -1, 0
	v_cndmask_b32_e64 v137, v2, 1.0, s[2:3]
	v_cmp_gt_f32_e32 vcc, 1.0, v137
	s_cbranch_vccz .LBB0_3447
	s_and_saveexec_b64 s[22:23], s[0:1]
	ds_write_b32 v153, v137 offset:128
	s_or_b64 exec, exec, s[22:23]
	s_waitcnt lgkmcnt(0)
	ds_read_b128 v[2:5], v154 offset:224
	ds_read_b128 v[6:9], v154 offset:192
	ds_read_b128 v[52:55], v154 offset:160
	ds_read_b128 v[56:59], v154 offset:128
	s_waitcnt lgkmcnt(0)
	v_pk_mul_f32 v[16:17], v[4:5], 0 op_sel_hi:[1,0]
	v_pk_mul_f32 v[12:13], v[8:9], 0 op_sel_hi:[1,0]
	v_pk_mul_f32 v[8:9], v[54:55], 0 op_sel_hi:[1,0]
	v_pk_mul_f32 v[4:5], v[58:59], 0 op_sel_hi:[1,0]
	v_pk_mul_f32 v[14:15], v[2:3], 0 op_sel_hi:[1,0]
	v_pk_mul_f32 v[10:11], v[6:7], 0 op_sel_hi:[1,0]
	v_pk_mul_f32 v[6:7], v[52:53], 0 op_sel_hi:[1,0]
	v_pk_mul_f32 v[2:3], v[56:57], 0 op_sel_hi:[1,0]
	s_branch .LBB0_3448

.LBB0_3448:
	v_cndmask_b32_e64 v158, v50, v156, s[2:3]
	v_mul_f32_e32 v50, 0xbe0293ee, v158
	v_fmamk_f32 v34, v34, 0x3e0293ee, v50
	v_exp_f32_e32 v34, v34
	v_fmamk_f32 v35, v35, 0x3e0293ee, v50
	v_exp_f32_e32 v35, v35
	v_fmamk_f32 v36, v36, 0x3e0293ee, v50
	v_exp_f32_e32 v36, v36
	v_fmamk_f32 v37, v37, 0x3e0293ee, v50
	v_exp_f32_e32 v37, v37
	v_fmamk_f32 v38, v38, 0x3e0293ee, v50
	v_fmamk_f32 v39, v39, 0x3e0293ee, v50
	v_fmamk_f32 v40, v40, 0x3e0293ee, v50
	v_fmamk_f32 v41, v41, 0x3e0293ee, v50
	v_fmamk_f32 v42, v42, 0x3e0293ee, v50
	v_fmamk_f32 v43, v43, 0x3e0293ee, v50
	v_fmamk_f32 v44, v44, 0x3e0293ee, v50
	v_fmamk_f32 v45, v45, 0x3e0293ee, v50
	v_fmamk_f32 v46, v46, 0x3e0293ee, v50
	v_fmamk_f32 v47, v47, 0x3e0293ee, v50
	v_fmamk_f32 v48, v48, 0x3e0293ee, v50
	v_fmamk_f32 v49, v49, 0x3e0293ee, v50
	v_fmamk_f32 v18, v18, 0x3e0293ee, v50
	v_fmamk_f32 v19, v19, 0x3e0293ee, v50
	v_fmamk_f32 v20, v20, 0x3e0293ee, v50
	v_fmamk_f32 v21, v21, 0x3e0293ee, v50
	v_fmamk_f32 v22, v22, 0x3e0293ee, v50
	v_fmamk_f32 v23, v23, 0x3e0293ee, v50
	v_fmamk_f32 v24, v24, 0x3e0293ee, v50
	v_fmamk_f32 v25, v25, 0x3e0293ee, v50
	v_fmamk_f32 v26, v26, 0x3e0293ee, v50
	v_fmamk_f32 v27, v27, 0x3e0293ee, v50
	v_fmamk_f32 v28, v28, 0x3e0293ee, v50
	v_fmamk_f32 v29, v29, 0x3e0293ee, v50
	v_fmamk_f32 v30, v30, 0x3e0293ee, v50
	v_fmamk_f32 v31, v31, 0x3e0293ee, v50
	v_fmamk_f32 v32, v32, 0x3e0293ee, v50
	v_fmac_f32_e32 v50, 0x3e0293ee, v33
	v_exp_f32_e32 v38, v38
	v_exp_f32_e32 v33, v50
	v_add_f32_e32 v50, 0, v34
	v_exp_f32_e32 v39, v39
	v_add_f32_e32 v50, v35, v50
	v_exp_f32_e32 v40, v40
	v_add_f32_e32 v50, v36, v50
	v_exp_f32_e32 v41, v41
	v_add_f32_e32 v50, v37, v50
	v_exp_f32_e32 v42, v42
	v_add_f32_e32 v50, v38, v50
	v_exp_f32_e32 v43, v43
	v_add_f32_e32 v50, v39, v50
	v_exp_f32_e32 v44, v44
	v_add_f32_e32 v50, v40, v50
	v_exp_f32_e32 v45, v45
	v_add_f32_e32 v50, v41, v50
	v_exp_f32_e32 v46, v46
	v_add_f32_e32 v50, v42, v50
	v_exp_f32_e32 v47, v47
	v_add_f32_e32 v50, v43, v50
	v_exp_f32_e32 v48, v48
	v_add_f32_e32 v50, v44, v50
	v_exp_f32_e32 v49, v49
	v_add_f32_e32 v50, v45, v50
	v_exp_f32_e32 v18, v18
	v_add_f32_e32 v50, v46, v50
	v_exp_f32_e32 v19, v19
	v_add_f32_e32 v50, v47, v50
	v_exp_f32_e32 v20, v20
	v_add_f32_e32 v50, v48, v50
	v_exp_f32_e32 v21, v21
	v_add_f32_e32 v50, v49, v50
	v_exp_f32_e32 v22, v22
	v_add_f32_e32 v50, v18, v50
	v_exp_f32_e32 v23, v23
	v_add_f32_e32 v50, v19, v50
	v_exp_f32_e32 v24, v24
	v_add_f32_e32 v50, v20, v50
	v_exp_f32_e32 v25, v25
	v_add_f32_e32 v50, v21, v50
	v_exp_f32_e32 v26, v26
	v_add_f32_e32 v50, v22, v50
	v_exp_f32_e32 v27, v27
	v_add_f32_e32 v50, v23, v50
	v_exp_f32_e32 v28, v28
	v_add_f32_e32 v50, v24, v50
	v_exp_f32_e32 v29, v29
	v_add_f32_e32 v50, v25, v50
	v_exp_f32_e32 v30, v30
	v_add_f32_e32 v50, v26, v50
	v_exp_f32_e32 v31, v31
	v_add_f32_e32 v50, v27, v50
	v_exp_f32_e32 v32, v32
	v_add_f32_e32 v50, v28, v50
	v_add_f32_e32 v50, v29, v50
	v_add_f32_e32 v50, v30, v50
	v_add_f32_e32 v50, v31, v50
	v_add_f32_e32 v50, v32, v50
	v_add_f32_e32 v159, v33, v50
	v_mov_b32_e32 v160, v159
	v_cvt_pk_bf16_f32 v74, v34, v35
	v_cvt_pk_bf16_f32 v75, v36, v37
	v_cvt_pk_bf16_f32 v76, v38, v39
	v_cvt_pk_bf16_f32 v77, v40, v41
	v_cvt_pk_bf16_f32 v78, v42, v43
	v_cvt_pk_bf16_f32 v79, v44, v45
	v_cvt_pk_bf16_f32 v80, v46, v47
	v_cvt_pk_bf16_f32 v81, v48, v49
	v_cvt_pk_bf16_f32 v82, v18, v19
	v_cvt_pk_bf16_f32 v83, v20, v21
	v_cvt_pk_bf16_f32 v84, v22, v23
	v_cvt_pk_bf16_f32 v85, v24, v25
	v_cvt_pk_bf16_f32 v86, v26, v27
	v_cvt_pk_bf16_f32 v87, v28, v29
	v_cvt_pk_bf16_f32 v88, v30, v31
	v_cvt_pk_bf16_f32 v89, v32, v33
	s_lshl_b64 s[20:21], s[20:21], 11
	s_lshl_b32 s43, s24, 7
	v_permlane32_swap_b32_e32 v159, v160
	v_permlane32_swap_b32_e32 v74, v76
	v_permlane32_swap_b32_e32 v75, v77
	v_permlane32_swap_b32_e32 v78, v80
	v_permlane32_swap_b32_e32 v79, v81
	v_permlane32_swap_b32_e32 v82, v84
	v_permlane32_swap_b32_e32 v83, v85
	v_permlane32_swap_b32_e32 v86, v88
	v_permlane32_swap_b32_e32 v87, v89
	ds_read_b64_tr_b16 v[34:35], v138 offset:0
	ds_read_b64_tr_b16 v[36:37], v138 offset:0x800
	ds_read_b64_tr_b16 v[38:39], v138 offset:0x1000
	ds_read_b64_tr_b16 v[40:41], v138 offset:0x1800
	ds_read_b64_tr_b16 v[42:43], v138 offset:0x2000
	ds_read_b64_tr_b16 v[44:45], v138 offset:0x2800
	ds_read_b64_tr_b16 v[46:47], v138 offset:0x3000
	ds_read_b64_tr_b16 v[48:49], v138 offset:0x3800
	ds_read_b64_tr_b16 v[50:51], v138 offset:0x200
	ds_read_b64_tr_b16 v[52:53], v138 offset:0xa00
	ds_read_b64_tr_b16 v[54:55], v138 offset:0x1200
	ds_read_b64_tr_b16 v[56:57], v138 offset:0x1a00
	ds_read_b64_tr_b16 v[58:59], v138 offset:0x2200
	ds_read_b64_tr_b16 v[60:61], v138 offset:0x2a00
	ds_read_b64_tr_b16 v[62:63], v138 offset:0x3200
	ds_read_b64_tr_b16 v[64:65], v138 offset:0x3a00
	s_waitcnt lgkmcnt(8)
	s_nop 0
	v_mfma_f32_32x32x16_bf16 v[18:33], v[74:77], v[34:37], v[2:17]
	v_mfma_f32_32x32x16_bf16 v[18:33], v[78:81], v[38:41], v[18:33]
	v_mfma_f32_32x32x16_bf16 v[18:33], v[82:85], v[42:45], v[18:33]
	v_mfma_f32_32x32x16_bf16 v[18:33], v[86:89], v[46:49], v[18:33]
	ds_read_b64_tr_b16 v[90:91], v138 offset:0x400
	ds_read_b64_tr_b16 v[92:93], v138 offset:0xc00
	ds_read_b64_tr_b16 v[94:95], v138 offset:0x1400
	ds_read_b64_tr_b16 v[96:97], v138 offset:0x1c00
	ds_read_b64_tr_b16 v[162:163], v138 offset:0x2400
	ds_read_b64_tr_b16 v[164:165], v138 offset:0x2c00
	ds_read_b64_tr_b16 v[166:167], v138 offset:0x3400
	ds_read_b64_tr_b16 v[168:169], v138 offset:0x3c00
	s_waitcnt lgkmcnt(8)
	v_mfma_f32_32x32x16_bf16 v[34:49], v[74:77], v[50:53], v[2:17]
	v_mfma_f32_32x32x16_bf16 v[34:49], v[78:81], v[54:57], v[34:49]
	v_mfma_f32_32x32x16_bf16 v[34:49], v[82:85], v[58:61], v[34:49]
	v_mfma_f32_32x32x16_bf16 v[34:49], v[86:89], v[62:65], v[34:49]
	ds_read_b64_tr_b16 v[170:171], v138 offset:0x600
	ds_read_b64_tr_b16 v[172:173], v138 offset:0xe00
	ds_read_b64_tr_b16 v[174:175], v138 offset:0x1600
	ds_read_b64_tr_b16 v[176:177], v138 offset:0x1e00
	ds_read_b64_tr_b16 v[178:179], v138 offset:0x2600
	ds_read_b64_tr_b16 v[180:181], v138 offset:0x2e00
	ds_read_b64_tr_b16 v[182:183], v138 offset:0x3600
	ds_read_b64_tr_b16 v[184:185], v138 offset:0x3e00
	s_waitcnt lgkmcnt(8)
	v_mfma_f32_32x32x16_bf16 v[50:65], v[74:77], v[90:93], v[2:17]
	v_mfma_f32_32x32x16_bf16 v[50:65], v[78:81], v[94:97], v[50:65]
	v_mfma_f32_32x32x16_bf16 v[50:65], v[82:85], v[162:165], v[50:65]
	v_mfma_f32_32x32x16_bf16 v[50:65], v[86:89], v[166:169], v[50:65]
	s_waitcnt lgkmcnt(0)
	v_mfma_f32_32x32x16_bf16 v[2:17], v[74:77], v[170:173], v[2:17]
	v_mfma_f32_32x32x16_bf16 v[2:17], v[78:81], v[174:177], v[2:17]
	v_mfma_f32_32x32x16_bf16 v[2:17], v[82:85], v[178:181], v[2:17]
	v_mfma_f32_32x32x16_bf16 v[2:17], v[86:89], v[182:185], v[2:17]
	v_readfirstlane_b32 s2, v70
	v_lshl_add_u64 v[74:75], v[66:67], 0, s[16:17]
	s_mov_b32 m0, s2
	v_readfirstlane_b32 s2, v71
	s_waitcnt vmcnt(4)
	s_nop 0
	s_barrier
	global_load_lds_dwordx4 v[74:75], off
	v_lshl_add_u64 v[66:67], v[66:67], 0, s[18:19]
	s_mov_b32 m0, s2
	v_readfirstlane_b32 s2, v151
	global_load_lds_dwordx4 v[66:67], off
	v_lshl_add_u64 v[66:67], v[68:69], 0, s[16:17]
	s_mov_b32 m0, s2
	v_readfirstlane_b32 s2, v72
	global_load_lds_dwordx4 v[66:67], off
	v_lshl_add_u64 v[66:67], v[68:69], 0, s[18:19]
	s_mov_b32 m0, s2
	s_nop 0
	global_load_lds_dwordx4 v[66:67], off
	v_mov_b32_e32 v161, v139
	v_mov_b32_e32 v198, v141
	s_nop 0
	v_xad_u32 v70, v198, v142, v161
	v_xad_u32 v74, v198, v146, v161
	ds_read_b128 v[66:69], v70
	ds_read_b128 v[70:73], v70 offset:8192
	ds_read_b128 v[162:165], v74
	ds_read_b128 v[166:169], v74 offset:8192
	v_xad_u32 v74, v198, v143, v161
	ds_read_b128 v[170:173], v74
	ds_read_b128 v[174:177], v74 offset:8192
	v_xad_u32 v74, v198, v147, v161
	ds_read_b128 v[178:181], v74
	ds_read_b128 v[182:185], v74 offset:8192
	s_waitcnt lgkmcnt(0)
	v_mfma_f32_32x32x16_bf16 v[82:97], v[66:69], v[98:101], 0
	v_xad_u32 v186, v198, v144, v161
	v_xad_u32 v194, v198, v148, v161
	v_mfma_f32_32x32x16_bf16 v[66:81], v[70:73], v[98:101], 0
	v_mfma_f32_32x32x16_bf16 v[82:97], v[162:165], v[102:105], v[82:97]
	ds_read_b128 v[162:165], v186
	ds_read_b128 v[186:189], v186 offset:8192
	ds_read_b128 v[190:193], v194
	ds_read_b128 v[194:197], v194 offset:8192
	v_mfma_f32_32x32x16_bf16 v[66:81], v[166:169], v[102:105], v[66:81]
	v_mfma_f32_32x32x16_bf16 v[82:97], v[170:173], v[106:109], v[82:97]
	v_xad_u32 v170, v198, v145, v161
	v_xad_u32 v161, v198, v149, v161
	ds_read_b128 v[166:169], v170
	ds_read_b128 v[170:173], v170 offset:8192
	v_mfma_f32_32x32x16_bf16 v[66:81], v[174:177], v[106:109], v[66:81]
	v_mfma_f32_32x32x16_bf16 v[82:97], v[178:181], v[110:113], v[82:97]
	ds_read_b128 v[174:177], v161
	ds_read_b128 v[178:181], v161 offset:8192
	v_mfma_f32_32x32x16_bf16 v[66:81], v[182:185], v[110:113], v[66:81]
	s_waitcnt lgkmcnt(0)
	v_mfma_f32_32x32x16_bf16 v[82:97], v[162:165], v[114:117], v[82:97]
	v_mfma_f32_32x32x16_bf16 v[66:81], v[186:189], v[114:117], v[66:81]
	v_mfma_f32_32x32x16_bf16 v[82:97], v[190:193], v[118:121], v[82:97]
	v_mfma_f32_32x32x16_bf16 v[66:81], v[194:197], v[118:121], v[66:81]
	v_mfma_f32_32x32x16_bf16 v[82:97], v[166:169], v[122:125], v[82:97]
	v_mfma_f32_32x32x16_bf16 v[66:81], v[170:173], v[122:125], v[66:81]
	v_mfma_f32_32x32x16_bf16 v[82:97], v[174:177], v[126:129], v[82:97]
	v_mfma_f32_32x32x16_bf16 v[66:81], v[178:181], v[126:129], v[66:81]
	s_nop 10
	v_max_f32_e32 v161, v83, v83
	v_max_f32_e32 v162, v82, v82
	v_max_f32_e32 v161, v162, v161
	v_max3_f32 v161, v161, v84, v85
	v_max3_f32 v161, v161, v86, v87
	v_max3_f32 v161, v161, v88, v89
	v_max3_f32 v161, v161, v90, v91
	v_max3_f32 v161, v161, v92, v93
	v_max3_f32 v161, v161, v94, v95
	v_max3_f32 v161, v161, v96, v97
	v_max3_f32 v161, v161, v66, v67
	v_max3_f32 v161, v161, v68, v69
	v_max3_f32 v161, v161, v70, v71
	v_max3_f32 v161, v161, v72, v73
	v_max3_f32 v161, v161, v74, v75
	v_max3_f32 v161, v161, v76, v77
	v_max3_f32 v161, v161, v78, v79
	v_max3_f32 v161, v161, v80, v81
	v_mov_b32_e32 v162, v161
	s_nop 1
	v_permlane32_swap_b32_e32 v161, v162
	v_max_f32_e32 v162, v162, v162
	v_max_f32_e32 v161, v161, v161
	v_max_f32_e32 v161, v161, v162
	v_max_f32_e32 v162, v158, v158
	v_max_f32_e32 v162, v162, v161
	v_sub_f32_e32 v163, v161, v158
	v_sub_f32_e32 v161, v158, v162
	v_mul_f32_e32 v161, 0x3e0293ee, v161
	v_exp_f32_e32 v161, v161
	v_cmp_ge_f32_e32 vcc, s40, v163
	s_cmp_eq_u64 vcc, exec
	s_cselect_b64 s[2:3], -1, 0
	v_cndmask_b32_e64 v161, v161, 1.0, s[2:3]
	v_cmp_gt_f32_e32 vcc, 1.0, v161
	s_cbranch_vccz .LBB0_3452
	s_and_saveexec_b64 s[22:23], s[0:1]
	ds_write_b32 v153, v161 offset:128
	s_or_b64 exec, exec, s[22:23]
	s_waitcnt lgkmcnt(0)
	ds_read_b128 v[164:167], v154 offset:224
	ds_read_b128 v[168:171], v154 offset:192
	ds_read_b128 v[172:175], v154 offset:160
	ds_read_b128 v[176:179], v154 offset:128
	s_waitcnt lgkmcnt(0)
	v_pk_mul_f32 v[32:33], v[32:33], v[166:167]
	v_pk_mul_f32 v[28:29], v[28:29], v[170:171]
	v_pk_mul_f32 v[24:25], v[24:25], v[174:175]
	v_pk_mul_f32 v[20:21], v[20:21], v[178:179]
	v_pk_mul_f32 v[30:31], v[30:31], v[164:165]
	v_pk_mul_f32 v[26:27], v[26:27], v[168:169]
	v_pk_mul_f32 v[22:23], v[22:23], v[172:173]
	v_pk_mul_f32 v[18:19], v[18:19], v[176:177]
	v_pk_mul_f32 v[48:49], v[48:49], v[166:167]
	v_pk_mul_f32 v[44:45], v[44:45], v[170:171]
	v_pk_mul_f32 v[40:41], v[40:41], v[174:175]
	v_pk_mul_f32 v[36:37], v[36:37], v[178:179]
	v_pk_mul_f32 v[46:47], v[46:47], v[164:165]
	v_pk_mul_f32 v[42:43], v[42:43], v[168:169]
	v_pk_mul_f32 v[38:39], v[38:39], v[172:173]
	v_pk_mul_f32 v[34:35], v[34:35], v[176:177]
	v_pk_mul_f32 v[64:65], v[64:65], v[166:167]
	v_pk_mul_f32 v[60:61], v[60:61], v[170:171]
	v_pk_mul_f32 v[56:57], v[56:57], v[174:175]
	v_pk_mul_f32 v[52:53], v[52:53], v[178:179]
	v_pk_mul_f32 v[62:63], v[62:63], v[164:165]
	v_pk_mul_f32 v[58:59], v[58:59], v[168:169]
	v_pk_mul_f32 v[54:55], v[54:55], v[172:173]
	v_pk_mul_f32 v[50:51], v[50:51], v[176:177]
	v_pk_mul_f32 v[16:17], v[16:17], v[166:167]
	v_pk_mul_f32 v[12:13], v[12:13], v[170:171]
	v_pk_mul_f32 v[8:9], v[8:9], v[174:175]
	v_pk_mul_f32 v[4:5], v[4:5], v[178:179]
	v_pk_mul_f32 v[14:15], v[14:15], v[164:165]
	v_pk_mul_f32 v[10:11], v[10:11], v[168:169]
	v_pk_mul_f32 v[6:7], v[6:7], v[172:173]
	v_pk_mul_f32 v[2:3], v[2:3], v[176:177]

.LBB0_3457:
	s_lshl_b32 s45, s44, 14
	s_nop 0
	s_barrier
	v_add_u32_e32 v159, s45, v152
	v_mov_b32_e32 v196, v141
	s_nop 0
	v_xad_u32 v70, v196, v142, v159
	v_xad_u32 v74, v196, v146, v159
	ds_read_b128 v[66:69], v70
	ds_read_b128 v[70:73], v70 offset:8192
	ds_read_b128 v[160:163], v74
	ds_read_b128 v[164:167], v74 offset:8192
	v_xad_u32 v74, v196, v143, v159
	ds_read_b128 v[168:171], v74
	ds_read_b128 v[172:175], v74 offset:8192
	v_xad_u32 v74, v196, v147, v159
	ds_read_b128 v[176:179], v74
	ds_read_b128 v[180:183], v74 offset:8192
	s_waitcnt lgkmcnt(7)
	v_mfma_f32_32x32x16_bf16 v[82:97], v[66:69], v[98:101], 0
	v_xad_u32 v184, v196, v144, v159
	v_xad_u32 v192, v196, v148, v159
	s_waitcnt lgkmcnt(6)
	v_mfma_f32_32x32x16_bf16 v[66:81], v[70:73], v[98:101], 0
	s_waitcnt lgkmcnt(5)
	v_mfma_f32_32x32x16_bf16 v[82:97], v[160:163], v[102:105], v[82:97]
	ds_read_b128 v[160:163], v184
	ds_read_b128 v[184:187], v184 offset:8192
	ds_read_b128 v[188:191], v192
	ds_read_b128 v[192:195], v192 offset:8192
	s_waitcnt lgkmcnt(8)
	v_mfma_f32_32x32x16_bf16 v[66:81], v[164:167], v[102:105], v[66:81]
	s_waitcnt lgkmcnt(7)
	v_mfma_f32_32x32x16_bf16 v[82:97], v[168:171], v[106:109], v[82:97]
	v_xad_u32 v168, v196, v145, v159
	v_xad_u32 v159, v196, v149, v159
	ds_read_b128 v[164:167], v168
	ds_read_b128 v[168:171], v168 offset:8192
	s_waitcnt lgkmcnt(8)
	v_mfma_f32_32x32x16_bf16 v[66:81], v[172:175], v[106:109], v[66:81]
	s_waitcnt lgkmcnt(7)
	v_mfma_f32_32x32x16_bf16 v[82:97], v[176:179], v[110:113], v[82:97]
	ds_read_b128 v[172:175], v159
	ds_read_b128 v[176:179], v159 offset:8192
	s_waitcnt lgkmcnt(8)
	v_mfma_f32_32x32x16_bf16 v[66:81], v[180:183], v[110:113], v[66:81]
	s_waitcnt lgkmcnt(7)
	v_mfma_f32_32x32x16_bf16 v[82:97], v[160:163], v[114:117], v[82:97]
	s_waitcnt lgkmcnt(6)
	v_mfma_f32_32x32x16_bf16 v[66:81], v[184:187], v[114:117], v[66:81]
	s_waitcnt lgkmcnt(5)
	v_mfma_f32_32x32x16_bf16 v[82:97], v[188:191], v[118:121], v[82:97]
	s_waitcnt lgkmcnt(4)
	v_mfma_f32_32x32x16_bf16 v[66:81], v[192:195], v[118:121], v[66:81]
	s_waitcnt lgkmcnt(3)
	v_mfma_f32_32x32x16_bf16 v[82:97], v[164:167], v[122:125], v[82:97]
	s_waitcnt lgkmcnt(2)
	v_mfma_f32_32x32x16_bf16 v[66:81], v[168:171], v[122:125], v[66:81]
	s_waitcnt lgkmcnt(1)
	v_mfma_f32_32x32x16_bf16 v[82:97], v[172:175], v[126:129], v[82:97]
	s_waitcnt lgkmcnt(0)
	v_mfma_f32_32x32x16_bf16 v[66:81], v[176:179], v[126:129], v[66:81]
	s_nop 9
	v_max_f32_e32 v159, v83, v83
	v_max_f32_e32 v160, v82, v82
	v_max_f32_e32 v159, v160, v159
	v_max3_f32 v159, v159, v84, v85
	v_max3_f32 v159, v159, v86, v87
	v_max3_f32 v159, v159, v88, v89
	v_max3_f32 v159, v159, v90, v91
	v_max3_f32 v159, v159, v92, v93
	v_max3_f32 v159, v159, v94, v95
	v_max3_f32 v159, v159, v96, v97
	v_max3_f32 v159, v159, v66, v67
	v_max3_f32 v159, v159, v68, v69
	v_max3_f32 v159, v159, v70, v71
	v_max3_f32 v159, v159, v72, v73
	v_max3_f32 v159, v159, v74, v75
	v_max3_f32 v159, v159, v76, v77
	v_max3_f32 v159, v159, v78, v79
	v_max3_f32 v159, v159, v80, v81
	v_mov_b32_e32 v160, v159
	s_nop 1
	v_permlane32_swap_b32_e32 v159, v160
	v_max_f32_e32 v160, v160, v160
	v_max_f32_e32 v159, v159, v159
	v_max_f32_e32 v159, v159, v160
	v_max_f32_e32 v161, v137, v137
	v_sub_f32_e32 v160, v159, v137
	v_max_f32_e32 v159, v161, v159
	v_sub_f32_e32 v161, v137, v159
	v_mul_f32_e32 v161, 0x3e0293ee, v161
	v_exp_f32_e32 v161, v161
	v_cmp_ge_f32_e32 vcc, s40, v160
	s_cmp_eq_u64 vcc, exec
	s_cselect_b64 s[2:3], -1, 0
	v_cndmask_b32_e64 v160, v161, 1.0, s[2:3]
	v_cmp_gt_f32_e32 vcc, 1.0, v160
	s_cbranch_vccz .LBB0_3461
	s_and_saveexec_b64 s[24:25], s[0:1]
	ds_write_b32 v153, v160 offset:128
	s_or_b64 exec, exec, s[24:25]
	s_waitcnt lgkmcnt(0)
	ds_read_b128 v[162:165], v154 offset:224
	ds_read_b128 v[166:169], v154 offset:192
	ds_read_b128 v[170:173], v154 offset:160
	ds_read_b128 v[174:177], v154 offset:128
	s_waitcnt lgkmcnt(3)
	v_pk_mul_f32 v[32:33], v[32:33], v[164:165]
	s_waitcnt lgkmcnt(2)
	v_pk_mul_f32 v[28:29], v[28:29], v[168:169]
	s_waitcnt lgkmcnt(1)
	v_pk_mul_f32 v[24:25], v[24:25], v[172:173]
	s_waitcnt lgkmcnt(0)
	v_pk_mul_f32 v[20:21], v[20:21], v[176:177]
	v_pk_mul_f32 v[30:31], v[30:31], v[162:163]
	v_pk_mul_f32 v[26:27], v[26:27], v[166:167]
	v_pk_mul_f32 v[22:23], v[22:23], v[170:171]
	v_pk_mul_f32 v[18:19], v[18:19], v[174:175]
	v_pk_mul_f32 v[48:49], v[48:49], v[164:165]
	v_pk_mul_f32 v[44:45], v[44:45], v[168:169]
	v_pk_mul_f32 v[40:41], v[40:41], v[172:173]
	v_pk_mul_f32 v[36:37], v[36:37], v[176:177]
	v_pk_mul_f32 v[46:47], v[46:47], v[162:163]
	v_pk_mul_f32 v[42:43], v[42:43], v[166:167]
	v_pk_mul_f32 v[38:39], v[38:39], v[170:171]
	v_pk_mul_f32 v[34:35], v[34:35], v[174:175]
	v_pk_mul_f32 v[64:65], v[64:65], v[164:165]
	v_pk_mul_f32 v[60:61], v[60:61], v[168:169]
	v_pk_mul_f32 v[56:57], v[56:57], v[172:173]
	v_pk_mul_f32 v[52:53], v[52:53], v[176:177]
	v_pk_mul_f32 v[62:63], v[62:63], v[162:163]
	v_pk_mul_f32 v[58:59], v[58:59], v[166:167]
	v_pk_mul_f32 v[54:55], v[54:55], v[170:171]
	v_pk_mul_f32 v[50:51], v[50:51], v[174:175]
	v_pk_mul_f32 v[16:17], v[16:17], v[164:165]
	v_pk_mul_f32 v[12:13], v[12:13], v[168:169]
	v_pk_mul_f32 v[8:9], v[8:9], v[172:173]
	v_pk_mul_f32 v[4:5], v[4:5], v[176:177]
	v_pk_mul_f32 v[14:15], v[14:15], v[162:163]
	v_pk_mul_f32 v[10:11], v[10:11], v[166:167]
	v_pk_mul_f32 v[6:7], v[6:7], v[170:171]
	v_pk_mul_f32 v[2:3], v[2:3], v[174:175]
